# moved the w_out f32->bf16 transposition from the prologue phase to the scan workgroups idle tail in phase 4 (hand-written)
# baseline (speedup 1.0000x reference)
; #define LAS __attribute__((address_space(3)))
; __device__ __forceinline__ void phase_prologue(const Args& A, LAS unsigned char* lds, int gw, int NGW, int wave, int lane) {
;     ...
;         while (it < NITEMS) {
;             const bool zero = 4 * lane >= nvalid;
; #pragma unroll
;             for (int i = 0; i < 16; ++i) *(LAS f32x4*)(tile + (wave * 16 + i) * 260 + 4 * lane) = zero ? (f32x4){0.f, 0.f, 0.f, 0.f} : cur[i];
;             bf16* dcur = dst; const int kcur = kdst;
;             const int nx = it + G_;
;             if (nx < NITEMS) { P0_DECODE(nx, src, ldw, nvalid, dst, kdst);
.LBB0_54:
	v_cmp_gt_i32_e32 vcc, s16, v70
	v_add_u32_e32 v72, s0, v69
	s_mul_i32 s10, s30, 0x410
	s_waitcnt vmcnt(0)
	v_cndmask_b32_e32 v81, 0, v39, vcc
	v_cndmask_b32_e32 v80, 0, v38, vcc
	v_cndmask_b32_e32 v79, 0, v37, vcc
	v_cndmask_b32_e32 v78, 0, v36, vcc
	ds_write_b128 v72, v[78:81]
	v_cndmask_b32_e32 v81, 0, v35, vcc
	v_cndmask_b32_e32 v80, 0, v34, vcc
	v_cndmask_b32_e32 v79, 0, v33, vcc
	v_cndmask_b32_e32 v78, 0, v32, vcc
	v_add_u32_e32 v72, s10, v69
	ds_write_b128 v72, v[78:81]
	v_cndmask_b32_e32 v81, 0, v47, vcc
	v_cndmask_b32_e32 v80, 0, v46, vcc
	v_cndmask_b32_e32 v79, 0, v45, vcc
	v_cndmask_b32_e32 v78, 0, v44, vcc
	ds_write_b128 v72, v[78:81] offset:1040
	v_cndmask_b32_e32 v81, 0, v43, vcc
	v_cndmask_b32_e32 v80, 0, v42, vcc
	v_cndmask_b32_e32 v79, 0, v41, vcc
	v_cndmask_b32_e32 v78, 0, v40, vcc
	ds_write_b128 v72, v[78:81] offset:2080
	v_cndmask_b32_e32 v81, 0, v55, vcc
	v_cndmask_b32_e32 v80, 0, v54, vcc
	v_cndmask_b32_e32 v79, 0, v53, vcc
	v_cndmask_b32_e32 v78, 0, v52, vcc
	ds_write_b128 v72, v[78:81] offset:3120
	v_cndmask_b32_e32 v81, 0, v51, vcc
	v_cndmask_b32_e32 v80, 0, v50, vcc
	v_cndmask_b32_e32 v79, 0, v49, vcc
	v_cndmask_b32_e32 v78, 0, v48, vcc
	ds_write_b128 v72, v[78:81] offset:4160
	v_cndmask_b32_e32 v81, 0, v63, vcc
	v_cndmask_b32_e32 v80, 0, v62, vcc
	v_cndmask_b32_e32 v79, 0, v61, vcc
	v_cndmask_b32_e32 v78, 0, v60, vcc
	ds_write_b128 v72, v[78:81] offset:5200
	v_cndmask_b32_e32 v81, 0, v59, vcc
	v_cndmask_b32_e32 v80, 0, v58, vcc
	v_cndmask_b32_e32 v79, 0, v57, vcc
	v_cndmask_b32_e32 v78, 0, v56, vcc
	ds_write_b128 v72, v[78:81] offset:6240
	v_cndmask_b32_e32 v81, 0, v31, vcc
	v_cndmask_b32_e32 v80, 0, v30, vcc
	v_cndmask_b32_e32 v79, 0, v29, vcc
	v_cndmask_b32_e32 v78, 0, v28, vcc
	ds_write_b128 v72, v[78:81] offset:7280
	v_cndmask_b32_e32 v81, 0, v27, vcc
	v_cndmask_b32_e32 v80, 0, v26, vcc
	v_cndmask_b32_e32 v79, 0, v25, vcc
	v_cndmask_b32_e32 v78, 0, v24, vcc
	ds_write_b128 v72, v[78:81] offset:8320
	v_cndmask_b32_e32 v81, 0, v23, vcc
	v_cndmask_b32_e32 v80, 0, v22, vcc
	v_cndmask_b32_e32 v79, 0, v21, vcc
	v_cndmask_b32_e32 v78, 0, v20, vcc
	ds_write_b128 v72, v[78:81] offset:9360
	v_cndmask_b32_e32 v81, 0, v19, vcc
	v_cndmask_b32_e32 v80, 0, v18, vcc
	v_cndmask_b32_e32 v79, 0, v17, vcc
	v_cndmask_b32_e32 v78, 0, v16, vcc
	ds_write_b128 v72, v[78:81] offset:10400
	v_cndmask_b32_e32 v81, 0, v15, vcc
	v_cndmask_b32_e32 v80, 0, v14, vcc
	v_cndmask_b32_e32 v79, 0, v13, vcc
	v_cndmask_b32_e32 v78, 0, v12, vcc
	s_add_i32 s81, s81, s70
	s_cmpk_lt_i32 s81, 0x740
	s_cbranch_scc1 .Lp0_noskip
	s_sub_i32 s98, s81, s70
	s_cmpk_lt_i32 s98, 0x740
	s_cbranch_scc0 .Lp0_noskip
	s_addk_i32 s81, 0x200
	s_add_i32 s78, s78, 0x20000
	s_addk_i32 s80, 0x2000
	s_addk_i32 s75, 0x1000
.Lp0_noskip:
	ds_write_b128 v72, v[78:81] offset:11440
	v_cndmask_b32_e32 v81, 0, v11, vcc
	v_cndmask_b32_e32 v80, 0, v10, vcc
	v_cndmask_b32_e32 v79, 0, v9, vcc
	v_cndmask_b32_e32 v78, 0, v8, vcc
	s_cmpk_gt_i32 s81, 0xa4b
	ds_write_b128 v72, v[78:81] offset:12480
	v_cndmask_b32_e32 v81, 0, v7, vcc
	v_cndmask_b32_e32 v80, 0, v6, vcc
	v_cndmask_b32_e32 v79, 0, v5, vcc
	v_cndmask_b32_e32 v78, 0, v4, vcc
	s_cselect_b64 s[10:11], -1, 0
	ds_write_b128 v72, v[78:81] offset:13520
	v_cndmask_b32_e32 v81, 0, v3, vcc
	v_cndmask_b32_e32 v80, 0, v2, vcc
	v_cndmask_b32_e32 v79, 0, v1, vcc
	v_cndmask_b32_e32 v78, 0, v0, vcc
	s_and_b64 vcc, exec, s[10:11]
	ds_write_b128 v72, v[78:81] offset:14560
	s_cbranch_vccnz .LBB0_53
	s_cmpk_gt_i32 s81, 0x73f
	s_mov_b64 s[16:17], -1
	s_cbranch_scc0 .LBB0_68
	s_cmpk_gt_u32 s81, 0x93f
	s_cbranch_scc0 .LBB0_65
	s_cmpk_gt_u32 s81, 0xa3f
	s_mov_b64 s[12:13], -1
	s_cbranch_scc0 .LBB0_63
	s_cmpk_gt_u32 s81, 0xa45
	s_cbranch_scc0 .LBB0_60
	s_load_dwordx16 s[36:51], s[62:63], 0x40
	s_add_i32 s6, s78, 0xfff5ba00
	s_lshl_b64 s[8:9], s[6:7], 2
	s_mov_b64 s[12:13], 0
	s_waitcnt lgkmcnt(0)
	s_add_u32 s14, s36, s8
	s_addc_u32 s15, s37, s9
	s_lshl_b64 s[8:9], s[6:7], 8
	v_readlane_b32 s6, v254, 30
	s_add_u32 s8, s6, s8
	v_readlane_b32 s6, v254, 31
	s_addc_u32 s9, s6, s9

; #define GAS __attribute__((address_space(1)))
; #define LAS __attribute__((address_space(3)))
; __device__ __forceinline__ unsigned pk2(float lo, float hi) { return f2bf(lo) | (f2bf(hi) << 16); }
; __device__ __forceinline__ void phase_prologue(const Args& A, LAS unsigned char* lds, int gw, int NGW, int wave, int lane) {
;     ...
;             { const int n = wave * 32 + (lane & 31);
; #pragma unroll
;               for (int i = 0; i < 8; ++i) { const int c = (lane >> 5) + 2 * i; const LAS float* tp = tile + (8 * c) * 260 + n;
;                   v4u o; o.x = pk2(tp[0], tp[260]); o.y = pk2(tp[2 * 260], tp[3 * 260]); o.z = pk2(tp[4 * 260], tp[5 * 260]); o.w = pk2(tp[6 * 260], tp[7 * 260]);
;                   *(GAS v4u*)(dcur + (size_t)n * kcur + 8 * c) = o; } }
; __global__ void __launch_bounds__(NWAVES * 64, 2) hybrid_fwd(Args A) {
;     ...
;         if (G >= 256) { if ((vcu & 31) < 12 && vcu < 256) sidx = (vcu >> 5) * 12 + (vcu & 31); }
;         if (!(A.flags & 1)) {
;             if (sidx >= 0) scan_unit(A, lds, sidx, tid);
;             else if (G < 256) { for (int s = bx; s < 96; s += G) scan_unit(A, lds, s, tid); }
;         }
;         if (!(A.flags & 2)) {
.LBB0_511:
	s_cmp_gt_u32 s97, 95
	s_cbranch_scc1 .Lwo_done
	s_load_dwordx2 s[4:5], s[62:63], 0x88
	v_mbcnt_lo_u32_b32 v64, -1, 0
	v_mbcnt_hi_u32_b32 v64, -1, v64
	v_readlane_b32 s0, v254, 8
	s_nop 3
	s_lshr_b32 s0, s0, 6
	v_lshlrev_b32_e32 v65, 4, v64
	s_lshl_b32 s1, s0, 18
	v_add_u32_e32 v65, s1, v65
	s_mul_i32 s1, s0, 0x4100
	v_lshlrev_b32_e32 v66, 4, v64
	v_add_u32_e32 v66, s1, v66
	v_and_b32_e32 v67, 31, v64
	s_lshl_b32 s1, s0, 5
	v_add_u32_e32 v67, s1, v67
	v_lshrrev_b32_e32 v68, 5, v64
	v_mul_u32_u24_e32 v69, 0x2080, v68
	v_lshl_add_u32 v69, v67, 2, v69
	v_add_u32_e32 v70, 0x10400, v69
	v_lshlrev_b32_e32 v71, 13, v67
	v_lshl_add_u32 v71, v68, 4, v71
	s_mov_b32 s2, s97
	s_waitcnt lgkmcnt(0)
; #define GAS __attribute__((address_space(1)))
; #define LAS __attribute__((address_space(3)))
; #define LDS_WAIT() asm volatile("s_waitcnt lgkmcnt(0)" ::: "memory")
; __device__ __forceinline__ unsigned pk2(float lo, float hi) { return f2bf(lo) | (f2bf(hi) << 16); }
; __device__ __forceinline__ void phase_prologue(const Args& A, LAS unsigned char* lds, int gw, int NGW, int wave, int lane) {
;     ...
;         while (it < NITEMS) {
;             const bool zero = 4 * lane >= nvalid;
; #pragma unroll
;             for (int i = 0; i < 16; ++i) *(LAS f32x4*)(tile + (wave * 16 + i) * 260 + 4 * lane) = zero ? (f32x4){0.f, 0.f, 0.f, 0.f} : cur[i];
;             bf16* dcur = dst; const int kcur = kdst;
;             const int nx = it + G_;
;             if (nx < NITEMS) { P0_DECODE(nx, src, ldw, nvalid, dst, kdst);
; #pragma unroll
;                 for (int i = 0; i < 16; ++i) cur[i] = __builtin_nontemporal_load((const f32x4*)(src + (size_t)(wave * 16 + i) * ldw + 4 * lane));     }
;             LDS_WAIT(); __syncthreads();
;             { const int n = wave * 32 + (lane & 31);
; #pragma unroll
;               for (int i = 0; i < 8; ++i) { const int c = (lane >> 5) + 2 * i; const LAS float* tp = tile + (8 * c) * 260 + n;
;                   v4u o; o.x = pk2(tp[0], tp[260]); o.y = pk2(tp[2 * 260], tp[3 * 260]); o.z = pk2(tp[4 * 260], tp[5 * 260]); o.w = pk2(tp[6 * 260], tp[7 * 260]);
;                   *(GAS v4u*)(dcur + (size_t)n * kcur + 8 * c) = o; } }
;             LDS_WAIT(); __syncthreads();
.Lwo_item:
	s_lshr_b32 s6, s2, 4
	s_and_b32 s7, s2, 15
	s_lshl_b32 s8, s6, 21
	s_lshl_b32 s9, s7, 10
	s_add_u32 s8, s8, s9
	s_add_u32 s20, s4, s8
	s_addc_u32 s21, s5, 0
	s_lshl_b32 s8, s7, 21
	s_lshl_b32 s9, s6, 8
	s_add_u32 s8, s8, s9
	s_add_u32 s8, s8, 0xb500000
	s_add_u32 s22, s34, s8
	s_addc_u32 s23, s35, 0
	global_load_dwordx4 v[0:3], v65, s[20:21]
	s_add_u32 s20, s20, 0x4000
	s_addc_u32 s21, s21, 0
	global_load_dwordx4 v[4:7], v65, s[20:21]
	s_add_u32 s20, s20, 0x4000
	s_addc_u32 s21, s21, 0
	global_load_dwordx4 v[8:11], v65, s[20:21]
	s_add_u32 s20, s20, 0x4000
	s_addc_u32 s21, s21, 0
	global_load_dwordx4 v[12:15], v65, s[20:21]
	s_add_u32 s20, s20, 0x4000
	s_addc_u32 s21, s21, 0
	global_load_dwordx4 v[16:19], v65, s[20:21]
	s_add_u32 s20, s20, 0x4000
	s_addc_u32 s21, s21, 0
	global_load_dwordx4 v[20:23], v65, s[20:21]
	s_add_u32 s20, s20, 0x4000
	s_addc_u32 s21, s21, 0
	global_load_dwordx4 v[24:27], v65, s[20:21]
	s_add_u32 s20, s20, 0x4000
	s_addc_u32 s21, s21, 0
	global_load_dwordx4 v[28:31], v65, s[20:21]
	s_add_u32 s20, s20, 0x4000
	s_addc_u32 s21, s21, 0
	global_load_dwordx4 v[32:35], v65, s[20:21]
	s_add_u32 s20, s20, 0x4000
	s_addc_u32 s21, s21, 0
	global_load_dwordx4 v[36:39], v65, s[20:21]
	s_add_u32 s20, s20, 0x4000
	s_addc_u32 s21, s21, 0
	global_load_dwordx4 v[40:43], v65, s[20:21]
	s_add_u32 s20, s20, 0x4000
	s_addc_u32 s21, s21, 0
	global_load_dwordx4 v[44:47], v65, s[20:21]
	s_add_u32 s20, s20, 0x4000
	s_addc_u32 s21, s21, 0
	global_load_dwordx4 v[48:51], v65, s[20:21]
	s_add_u32 s20, s20, 0x4000
	s_addc_u32 s21, s21, 0
	global_load_dwordx4 v[52:55], v65, s[20:21]
	s_add_u32 s20, s20, 0x4000
	s_addc_u32 s21, s21, 0
	global_load_dwordx4 v[56:59], v65, s[20:21]
	s_add_u32 s20, s20, 0x4000
	s_addc_u32 s21, s21, 0
	global_load_dwordx4 v[60:63], v65, s[20:21]
	s_waitcnt vmcnt(15)
	ds_write_b128 v66, v[0:3]
	s_waitcnt vmcnt(14)
	ds_write_b128 v66, v[4:7] offset:1040
	s_waitcnt vmcnt(13)
	ds_write_b128 v66, v[8:11] offset:2080
	s_waitcnt vmcnt(12)
	ds_write_b128 v66, v[12:15] offset:3120
	s_waitcnt vmcnt(11)
	ds_write_b128 v66, v[16:19] offset:4160
	s_waitcnt vmcnt(10)
	ds_write_b128 v66, v[20:23] offset:5200
	s_waitcnt vmcnt(9)
	ds_write_b128 v66, v[24:27] offset:6240
	s_waitcnt vmcnt(8)
	ds_write_b128 v66, v[28:31] offset:7280
	s_waitcnt vmcnt(7)
	ds_write_b128 v66, v[32:35] offset:8320
	s_waitcnt vmcnt(6)
	ds_write_b128 v66, v[36:39] offset:9360
	s_waitcnt vmcnt(5)
	ds_write_b128 v66, v[40:43] offset:10400
	s_waitcnt vmcnt(4)
	ds_write_b128 v66, v[44:47] offset:11440
	s_waitcnt vmcnt(3)
	ds_write_b128 v66, v[48:51] offset:12480
	s_waitcnt vmcnt(2)
	ds_write_b128 v66, v[52:55] offset:13520
	s_waitcnt vmcnt(1)
	ds_write_b128 v66, v[56:59] offset:14560
	s_waitcnt vmcnt(0)
	ds_write_b128 v66, v[60:63] offset:15600
	s_waitcnt lgkmcnt(0)
	s_barrier
	ds_read_b32 v72, v69
	ds_read_b32 v73, v69 offset:1040
	ds_read_b32 v74, v69 offset:2080
	ds_read_b32 v75, v69 offset:3120
	ds_read_b32 v76, v69 offset:4160
	ds_read_b32 v77, v69 offset:5200
	ds_read_b32 v78, v69 offset:6240
	ds_read_b32 v79, v69 offset:7280
	ds_read_b32 v80, v69 offset:16640
	ds_read_b32 v81, v69 offset:17680
	ds_read_b32 v82, v69 offset:18720
	ds_read_b32 v83, v69 offset:19760
	ds_read_b32 v84, v69 offset:20800
	ds_read_b32 v85, v69 offset:21840
	ds_read_b32 v86, v69 offset:22880
	ds_read_b32 v87, v69 offset:23920
	s_waitcnt lgkmcnt(8)
	v_cvt_pk_bf16_f32 v136, v72, v73
	v_cvt_pk_bf16_f32 v137, v74, v75
	v_cvt_pk_bf16_f32 v138, v76, v77
	v_cvt_pk_bf16_f32 v139, v78, v79
	global_store_dwordx4 v71, v[136:139], s[22:23]
	ds_read_b32 v88, v69 offset:33280
	ds_read_b32 v89, v69 offset:34320
	ds_read_b32 v90, v69 offset:35360
	ds_read_b32 v91, v69 offset:36400
	ds_read_b32 v92, v69 offset:37440
	ds_read_b32 v93, v69 offset:38480
	ds_read_b32 v94, v69 offset:39520
	ds_read_b32 v95, v69 offset:40560
	s_waitcnt lgkmcnt(8)
	v_cvt_pk_bf16_f32 v140, v80, v81
	v_cvt_pk_bf16_f32 v141, v82, v83
	v_cvt_pk_bf16_f32 v142, v84, v85
	v_cvt_pk_bf16_f32 v143, v86, v87
	global_store_dwordx4 v71, v[140:143], s[22:23] offset:32
	ds_read_b32 v96, v69 offset:49920
	ds_read_b32 v97, v69 offset:50960
	ds_read_b32 v98, v69 offset:52000
	ds_read_b32 v99, v69 offset:53040
	ds_read_b32 v100, v69 offset:54080
	ds_read_b32 v101, v69 offset:55120
	ds_read_b32 v102, v69 offset:56160
	ds_read_b32 v103, v69 offset:57200
	s_waitcnt lgkmcnt(8)
	v_cvt_pk_bf16_f32 v136, v88, v89
	v_cvt_pk_bf16_f32 v137, v90, v91
	v_cvt_pk_bf16_f32 v138, v92, v93
	v_cvt_pk_bf16_f32 v139, v94, v95
	global_store_dwordx4 v71, v[136:139], s[22:23] offset:64
	ds_read_b32 v104, v70
	ds_read_b32 v105, v70 offset:1040
	ds_read_b32 v106, v70 offset:2080
	ds_read_b32 v107, v70 offset:3120
	ds_read_b32 v108, v70 offset:4160
	ds_read_b32 v109, v70 offset:5200
	ds_read_b32 v110, v70 offset:6240
	ds_read_b32 v111, v70 offset:7280
	s_waitcnt lgkmcnt(8)
	v_cvt_pk_bf16_f32 v140, v96, v97
	v_cvt_pk_bf16_f32 v141, v98, v99
	v_cvt_pk_bf16_f32 v142, v100, v101
	v_cvt_pk_bf16_f32 v143, v102, v103
	global_store_dwordx4 v71, v[140:143], s[22:23] offset:96
	ds_read_b32 v112, v70 offset:16640
	ds_read_b32 v113, v70 offset:17680
	ds_read_b32 v114, v70 offset:18720
	ds_read_b32 v115, v70 offset:19760
	ds_read_b32 v116, v70 offset:20800
	ds_read_b32 v117, v70 offset:21840
	ds_read_b32 v118, v70 offset:22880
	ds_read_b32 v119, v70 offset:23920
	s_waitcnt lgkmcnt(8)
	v_cvt_pk_bf16_f32 v136, v104, v105
	v_cvt_pk_bf16_f32 v137, v106, v107
	v_cvt_pk_bf16_f32 v138, v108, v109
	v_cvt_pk_bf16_f32 v139, v110, v111
	global_store_dwordx4 v71, v[136:139], s[22:23] offset:128
	ds_read_b32 v120, v70 offset:33280
	ds_read_b32 v121, v70 offset:34320
	ds_read_b32 v122, v70 offset:35360
	ds_read_b32 v123, v70 offset:36400
	ds_read_b32 v124, v70 offset:37440
	ds_read_b32 v125, v70 offset:38480
	ds_read_b32 v126, v70 offset:39520
	ds_read_b32 v127, v70 offset:40560
	s_waitcnt lgkmcnt(8)
	v_cvt_pk_bf16_f32 v140, v112, v113
	v_cvt_pk_bf16_f32 v141, v114, v115
	v_cvt_pk_bf16_f32 v142, v116, v117
	v_cvt_pk_bf16_f32 v143, v118, v119
	global_store_dwordx4 v71, v[140:143], s[22:23] offset:160
	ds_read_b32 v128, v70 offset:49920
	ds_read_b32 v129, v70 offset:50960
	ds_read_b32 v130, v70 offset:52000
	ds_read_b32 v131, v70 offset:53040
	ds_read_b32 v132, v70 offset:54080
	ds_read_b32 v133, v70 offset:55120
	ds_read_b32 v134, v70 offset:56160
	ds_read_b32 v135, v70 offset:57200
	s_waitcnt lgkmcnt(8)
	v_cvt_pk_bf16_f32 v136, v120, v121
	v_cvt_pk_bf16_f32 v137, v122, v123
	v_cvt_pk_bf16_f32 v138, v124, v125
	v_cvt_pk_bf16_f32 v139, v126, v127
	global_store_dwordx4 v71, v[136:139], s[22:23] offset:192
	s_waitcnt lgkmcnt(0)
	v_cvt_pk_bf16_f32 v140, v128, v129
	v_cvt_pk_bf16_f32 v141, v130, v131
	v_cvt_pk_bf16_f32 v142, v132, v133
	v_cvt_pk_bf16_f32 v143, v134, v135
	global_store_dwordx4 v71, v[140:143], s[22:23] offset:224
	s_barrier
	s_add_i32 s2, s2, 0x60
	s_cmpk_lt_u32 s2, 0x200
	s_cbranch_scc1 .Lwo_item

; __global__ void __launch_bounds__(NWAVES * 64, 2) hybrid_fwd(Args A) {
	.amdhsa_kernel _Z10hybrid_fwd4Args
		.amdhsa_group_segment_fixed_size 0
		.amdhsa_private_segment_fixed_size 0
		.amdhsa_kernarg_size 440
		.amdhsa_user_sgpr_count 2
		.amdhsa_user_sgpr_dispatch_ptr 0
		.amdhsa_user_sgpr_queue_ptr 0
		.amdhsa_user_sgpr_kernarg_segment_ptr 1
		.amdhsa_user_sgpr_dispatch_id 0
		.amdhsa_user_sgpr_kernarg_preload_length 0
		.amdhsa_user_sgpr_kernarg_preload_offset 0
		.amdhsa_user_sgpr_private_segment_size 0
		.amdhsa_uses_dynamic_stack 0
		.amdhsa_enable_private_segment 0
		.amdhsa_system_sgpr_workgroup_id_x 1
		.amdhsa_system_sgpr_workgroup_id_y 0
		.amdhsa_system_sgpr_workgroup_id_z 0
		.amdhsa_system_sgpr_workgroup_info 0
		.amdhsa_system_vgpr_workitem_id 2
		.amdhsa_next_free_vgpr 255
		.amdhsa_next_free_sgpr 100
		.amdhsa_accum_offset 256
		.amdhsa_reserve_vcc 1
		.amdhsa_float_round_mode_32 0
		.amdhsa_float_round_mode_16_64 0
		.amdhsa_float_denorm_mode_32 3
		.amdhsa_float_denorm_mode_16_64 3
		.amdhsa_dx10_clamp 1
		.amdhsa_ieee_mode 1
		.amdhsa_fp16_overflow 0
		.amdhsa_tg_split 0
		.amdhsa_exception_fp_ieee_invalid_op 0
		.amdhsa_exception_fp_denorm_src 0
		.amdhsa_exception_fp_ieee_div_zero 0
		.amdhsa_exception_fp_ieee_overflow 0
		.amdhsa_exception_fp_ieee_underflow 0
		.amdhsa_exception_fp_ieee_inexact 0
		.amdhsa_exception_int_div_zero 0
	.end_amdhsa_kernel

; __global__ void __launch_bounds__(NWAVES * 64, 2) hybrid_fwd(Args A) {
amdhsa.kernels:
  - .agpr_count:     0
    .args:
      - .offset:         0
        .size:           184
        .value_kind:     by_value
      - .offset:         184
        .size:           4
        .value_kind:     hidden_block_count_x
      - .offset:         188
        .size:           4
        .value_kind:     hidden_block_count_y
      - .offset:         192
        .size:           4
        .value_kind:     hidden_block_count_z
      - .offset:         196
        .size:           2
        .value_kind:     hidden_group_size_x
      - .offset:         198
        .size:           2
        .value_kind:     hidden_group_size_y
      - .offset:         200
        .size:           2
        .value_kind:     hidden_group_size_z
      - .offset:         202
        .size:           2
        .value_kind:     hidden_remainder_x
      - .offset:         204
        .size:           2
        .value_kind:     hidden_remainder_y
      - .offset:         206
        .size:           2
        .value_kind:     hidden_remainder_z
      - .offset:         224
        .size:           8
        .value_kind:     hidden_global_offset_x
      - .offset:         232
        .size:           8
        .value_kind:     hidden_global_offset_y
      - .offset:         240
        .size:           8
        .value_kind:     hidden_global_offset_z
      - .offset:         248
        .size:           2
        .value_kind:     hidden_grid_dims
      - .offset:         272
        .size:           8
        .value_kind:     hidden_multigrid_sync_arg
      - .offset:         304
        .size:           4
        .value_kind:     hidden_dynamic_lds_size
    .group_segment_fixed_size: 0
    .kernarg_segment_align: 8
    .kernarg_segment_size: 440
    .language:       OpenCL C
    .language_version:
      - 2
      - 0
    .max_flat_workgroup_size: 512
    .name:           _Z10hybrid_fwd4Args
    .private_segment_fixed_size: 0
    .sgpr_count:     106
    .sgpr_spill_count: 34
    .symbol:         _Z10hybrid_fwd4Args.kd
    .uniform_work_group_size: 1
    .uses_dynamic_stack: false
    .vgpr_count:     255
    .vgpr_spill_count: 0
    .wavefront_size: 64
